# barrier poll loop without s_sleep between polls of the per-XCD generation word
# speedup vs baseline: 1.0051x; 1.0051x over previous
.LBB0_200:
	s_and_b32 s4, s16, 0xff
	s_mov_b64 s[26:27], -1
	s_cmp_lg_u32 s4, 0
	s_mov_b64 s[30:31], -1
	s_cbranch_scc1 .LBB0_203
	global_load_dword v0, v177, s[68:69] sc1
	s_waitcnt vmcnt(0)
	v_cmp_eq_u32_e32 vcc, 0, v0
	s_cbranch_vccnz .LBB0_205
	s_mov_b64 s[30:31], 0
	s_mov_b64 s[28:29], -1

.LBB0_350:
	s_and_b32 s4, s16, 0xff
	s_mov_b64 s[18:19], -1
	s_cmp_lg_u32 s4, 0
	s_mov_b64 s[22:23], -1
	s_cbranch_scc1 .LBB0_353
	global_load_dword v0, v177, s[50:51] sc1
	s_waitcnt vmcnt(0)
	v_cmp_eq_u32_e32 vcc, 0, v0
	s_cbranch_vccnz .LBB0_355
	s_mov_b64 s[22:23], 0
	s_mov_b64 s[20:21], -1

.LBB0_520:
	s_and_b32 s4, s16, 0xff
	s_mov_b64 s[18:19], -1
	s_cmp_lg_u32 s4, 0
	s_mov_b64 s[22:23], -1
	s_cbranch_scc1 .LBB0_523
	global_load_dword v0, v177, s[68:69] sc1
	s_waitcnt vmcnt(0)
	v_cmp_eq_u32_e32 vcc, 0, v0
	s_cbranch_vccnz .LBB0_525
	s_mov_b64 s[22:23], 0
	s_mov_b64 s[20:21], -1

.LBB0_749:
	s_and_b32 s18, s4, 0xff
	s_mov_b64 s[16:17], -1
	s_cmp_lg_u32 s18, 0
	s_mov_b64 s[22:23], -1
	s_cbranch_scc1 .LBB0_752
	global_load_dword v0, v181, s[68:69] sc1
	s_waitcnt vmcnt(0)
	v_cmp_eq_u32_e32 vcc, 0, v0
	s_cbranch_vccnz .LBB0_754
	s_mov_b64 s[22:23], 0
	s_mov_b64 s[20:21], -1

.LBB0_905:
	s_and_b32 s18, s4, 0xff
	s_mov_b64 s[16:17], -1
	s_cmp_lg_u32 s18, 0
	s_mov_b64 s[20:21], -1
	s_cbranch_scc1 .LBB0_908
	global_load_dword v0, v181, s[68:69] sc1
	s_waitcnt vmcnt(0)
	v_cmp_eq_u32_e32 vcc, 0, v0
	s_cbranch_vccnz .LBB0_910
	s_mov_b64 s[20:21], 0
	s_mov_b64 s[18:19], -1
